# v64 with packed fp32 ops (v_pk_mul_f32/v_pk_add_f32) between MFMAs split into scalar pairs in the recurrence and attention hot loops
# baseline (speedup 1.0000x reference)
; #define LAS __attribute__((address_space(3)))
; __device__ __forceinline__ void hg_recur(LAS unsigned char* lds, const bf16_t* QF, bf16_t* IG, const bf16_t* P, const float* Dg, float* ssq_o, int G, int bid) {
;     ...
;             for (int ss = 0; ss < 2; ++ss) {
;                 const LAS unsigned char* vp = sb + H3_V + (16 * ss + 4 * fq) * H3_VP + (16 * vt + lv) * 2;
;                 const unsigned e0 = *(const LAS bf16_t*)(vp), e1 = *(const LAS bf16_t*)(vp + H3_VP), e2 = *(const LAS bf16_t*)(vp + 2 * H3_VP), e3 = *(const LAS bf16_t*)(vp + 3 * H3_VP);
;                 vfu[ss].x = e0 | (e1 << 16); vfu[ss].y = e2 | (e3 << 16);
;             }
;             const s16x4 vf0 = __builtin_bit_cast(s16x4, vfu[0]), vf1 = __builtin_bit_cast(s16x4, vfu[1]);
.LBB0_504:
	ds_read2st64_b64 v[78:81], v90 offset0:32 offset1:40
	ds_read2st64_b64 v[112:115], v90 offset0:48 offset1:56
	ds_read_u16 v33, v98 offset:21504
	ds_read_u16 v39, v98 offset:21584
	ds_read_u16 v32, v98 offset:21664
	ds_read_u16 v34, v98 offset:21744
	ds_read_u16 v36, v98 offset:22784
	ds_read_u16 v35, v98 offset:22864
	ds_read_u16 v37, v98 offset:22944
	ds_read_u16 v38, v98 offset:23024
	s_waitcnt lgkmcnt(10)
	ds_read_b64 v[130:131], v99
	ds_read_b64 v[132:133], v99 offset:4352
	ds_read_b64 v[134:135], v99 offset:32
	ds_read_b64 v[136:137], v99 offset:4384
	s_waitcnt lgkmcnt(4)
	ds_read_b64 v[138:139], v100 offset:18944
	ds_read2_b64 v[140:143], v61 offset0:64 offset1:68
	ds_read_b128 v[144:147], v101 offset:24064
	ds_read_b128 v[148:151], v103 offset:24064
	ds_read2_b64 v[152:155], v107 offset0:64 offset1:68
	s_nop 0
	v_mov_b32_e32 v82, v78
	s_nop 0
	v_mov_b32_e32 v83, v112
	v_mov_b32_e32 v116, v80
	v_mov_b32_e32 v117, v114
	v_add_f32_e32 v82, v82, v116
	v_add_f32_e32 v83, v83, v117
	v_mov_b32_e32 v112, v79
	v_mov_b32_e32 v114, v81
	v_add_f32_e32 v73, v82, v83
	v_add_f32_e32 v78, v112, v114
	v_add_f32_e32 v79, v113, v115
	s_nop 0
	v_add_f32_e32 v80, v78, v79
	v_cvt_pk_bf16_f32 v81, v73, v80
	v_mul_f32_e32 v73, v73, v73
	v_fmac_f32_e32 v73, v80, v80
	v_add_co_u32_e32 v78, vcc, s3, v76
	s_nop 0
	v_add_f32_dpp v73, v73, v73 row_ror:8 row_mask:0xf bank_mask:0xf bound_ctrl:1
	v_addc_co_u32_e32 v79, vcc, -1, v77, vcc
	s_nop 0
	v_add_f32_dpp v73, v73, v73 row_ror:4 row_mask:0xf bank_mask:0xf bound_ctrl:1
	global_store_dword v[78:79], v81, off
	s_nop 0
	v_add_f32_dpp v73, v73, v73 row_ror:2 row_mask:0xf bank_mask:0xf bound_ctrl:1
	s_nop 1
	v_mov_b32_dpp v78, v73 row_ror:1 row_mask:0xf bank_mask:0xf bound_ctrl:1
	s_and_saveexec_b64 s[58:59], s[14:15]
	s_cbranch_execz .LBB0_506
	v_add_f32_e32 v73, v73, v78
	global_atomic_add_f32 v[74:75], v73, off offset:-1024

; #define LAS __attribute__((address_space(3)))
; #define LDS_BARRIER() do { asm volatile("s_waitcnt lgkmcnt(0)" ::: "memory"); __builtin_amdgcn_s_barrier(); asm volatile("" ::: "memory"); } while (0)
; __device__ __forceinline__ void hg_recur(LAS unsigned char* lds, const bf16_t* QF, bf16_t* IG, const bf16_t* P, const float* Dg, float* ssq_o, int G, int bid) {
;     ...
; #pragma unroll
;             for (int k2 = 0; k2 < 2; ++k2) {
;                 const f32x4 dd = *(const LAS f32x4*)(sb + H3_D + (32 * kq + 16 * k2 + 4 * fq) * 4);
;                 S[k2] = S[k2] * dd;
;                 const LAS unsigned char* kp = sb + H3_K + (32 * kq + 16 * k2 + lv) * H3_KP + 4 * fq * 2;
;                 const s16x4 a0 = *(const LAS s16x4*)kp, a1 = *(const LAS s16x4*)(kp + 32);
;                 S[k2] = __builtin_amdgcn_mfma_f32_16x16x16bf16_1k(a0, vf0, S[k2], 0, 0, 0);
;                 S[k2] = __builtin_amdgcn_mfma_f32_16x16x16bf16_1k(a1, vf1, S[k2], 0, 0, 0);
;             }
;             { LAS float* ot = (LAS float*)(lds + H3_O + st * H3_OBYTES) + kq * 1024 + 16 * vt + lv;
; #pragma unroll
;               for (int i = 0; i < 4; ++i) { ot[(4 * fq + i) * 32] = o0[i]; ot[(16 + 4 * fq + i) * 32] = o1[i]; } }
;             LDS_BARRIER();
.LBB0_516:
	s_or_b64 exec, exec, s[58:59]
	s_nop 0
	s_nop 0
	s_nop 0
	s_add_i32 s36, s35, 1
	s_cmpk_gt_u32 s36, 0xfe
	s_waitcnt lgkmcnt(2)
	v_mul_f32_e32 v30, v30, v146
	v_mul_f32_e32 v31, v31, v147
	v_mul_f32_e32 v28, v28, v144
	v_mul_f32_e32 v29, v29, v145
	s_nop 0
	s_waitcnt lgkmcnt(1)
	v_mul_f32_e32 v26, v26, v150
	v_mul_f32_e32 v27, v27, v151
	v_mul_f32_e32 v24, v24, v148
	v_mul_f32_e32 v25, v25, v149
	v_mfma_f32_16x16x16_bf16 v[28:31], v[140:141], v[78:79], v[28:31]
	ds_write2_b32 v92, v32, v33 offset1:32
	ds_write2_b32 v108, v36, v37 offset1:32
	ds_write2_b32 v92, v34, v35 offset0:64 offset1:96
	ds_write2_b32 v108, v38, v39 offset0:64 offset1:96
	s_waitcnt lgkmcnt(0)
	s_waitcnt lgkmcnt(4)
	v_mfma_f32_16x16x16_bf16 v[24:27], v[152:153], v[78:79], v[24:27]
	s_barrier
	v_mfma_f32_16x16x16_bf16 v[28:31], v[142:143], v[80:81], v[28:31]
	v_mfma_f32_16x16x16_bf16 v[24:27], v[154:155], v[80:81], v[24:27]
	s_cbranch_scc1 .LBB0_528
	s_waitcnt vmcnt(2)
	ds_write_b128 v105, v[8:11]
	s_waitcnt vmcnt(1)
	ds_write_b128 v97, v[12:15] offset:8704
	s_and_saveexec_b64 s[36:37], s[8:9]
	s_xor_b64 s[58:59], exec, s[36:37]
	s_cbranch_execz .LBB0_525
	s_and_saveexec_b64 s[36:37], s[10:11]
	s_xor_b64 s[60:61], exec, s[36:37]
	s_cbranch_execz .LBB0_522
	s_and_saveexec_b64 s[62:63], s[12:13]
	v_add_u32_e32 v32, 0, v86
	ds_write_b128 v32, v[0:3] offset:19968
	s_or_b64 exec, exec, s[62:63]

; #define LAS __attribute__((address_space(3)))
; __device__ __forceinline__ void hg_recur(LAS unsigned char* lds, const bf16_t* QF, bf16_t* IG, const bf16_t* P, const float* Dg, float* ssq_o, int G, int bid) {
;     ...
;             for (int ss = 0; ss < 2; ++ss) {
;                 const LAS unsigned char* vp = sb + H3_V + (16 * ss + 4 * fq) * H3_VP + (16 * vt + lv) * 2;
;                 const unsigned e0 = *(const LAS bf16_t*)(vp), e1 = *(const LAS bf16_t*)(vp + H3_VP), e2 = *(const LAS bf16_t*)(vp + 2 * H3_VP), e3 = *(const LAS bf16_t*)(vp + 3 * H3_VP);
;                 vfu[ss].x = e0 | (e1 << 16); vfu[ss].y = e2 | (e3 << 16);
;             }
;             const s16x4 vf0 = __builtin_bit_cast(s16x4, vfu[0]), vf1 = __builtin_bit_cast(s16x4, vfu[1]);
.LBB0_538:
	ds_read2st64_b64 v[78:81], v49 offset0:96 offset1:104
	ds_read2st64_b64 v[112:115], v49 offset0:112 offset1:120
	ds_read_u16 v33, v98 offset:46080
	ds_read_u16 v39, v98 offset:46160
	ds_read_u16 v32, v98 offset:46240
	ds_read_u16 v34, v98 offset:46320
	ds_read_u16 v36, v98 offset:47360
	ds_read_u16 v35, v98 offset:47440
	ds_read_u16 v37, v98 offset:47520
	ds_read_u16 v38, v98 offset:47600
	s_waitcnt lgkmcnt(10)
	ds_read_b64 v[130:131], v99 offset:24576
	ds_read_b64 v[132:133], v99 offset:28928
	ds_read_b64 v[134:135], v99 offset:24608
	ds_read_b64 v[136:137], v99 offset:28960
	s_waitcnt lgkmcnt(4)
	ds_read_b64 v[138:139], v100 offset:43520
	ds_read2_b64 v[140:143], v63 offset0:64 offset1:68
	ds_read_b128 v[144:147], v101 offset:48640
	ds_read_b128 v[148:151], v103 offset:48640
	ds_read2_b64 v[152:155], v109 offset0:64 offset1:68
	s_nop 0
	v_mov_b32_e32 v82, v78
	s_nop 0
	v_mov_b32_e32 v83, v112
	v_mov_b32_e32 v116, v80
	v_mov_b32_e32 v117, v114
	v_add_f32_e32 v82, v82, v116
	v_add_f32_e32 v83, v83, v117
	v_mov_b32_e32 v112, v79
	v_mov_b32_e32 v114, v81
	v_add_f32_e32 v73, v82, v83
	v_add_f32_e32 v78, v112, v114
	v_add_f32_e32 v79, v113, v115
	s_nop 0
	v_add_f32_e32 v78, v78, v79
	v_cvt_pk_bf16_f32 v79, v73, v78
	v_mul_f32_e32 v73, v73, v73
	v_fmac_f32_e32 v73, v78, v78
	global_store_dword v[76:77], v79, off
	s_nop 0
	v_add_f32_dpp v73, v73, v73 row_ror:8 row_mask:0xf bank_mask:0xf bound_ctrl:1
	s_nop 1
	v_add_f32_dpp v73, v73, v73 row_ror:4 row_mask:0xf bank_mask:0xf bound_ctrl:1
	s_nop 1
	v_add_f32_dpp v73, v73, v73 row_ror:2 row_mask:0xf bank_mask:0xf bound_ctrl:1
	s_nop 1
	v_mov_b32_dpp v78, v73 row_ror:1 row_mask:0xf bank_mask:0xf bound_ctrl:1
	s_and_saveexec_b64 s[56:57], s[14:15]
	s_cbranch_execz .LBB0_540
	v_add_f32_e32 v73, v73, v78
	global_atomic_add_f32 v[74:75], v73, off

; #define LAS __attribute__((address_space(3)))
; #define LDS_BARRIER() do { asm volatile("s_waitcnt lgkmcnt(0)" ::: "memory"); __builtin_amdgcn_s_barrier(); asm volatile("" ::: "memory"); } while (0)
; __device__ __forceinline__ void hg_recur(LAS unsigned char* lds, const bf16_t* QF, bf16_t* IG, const bf16_t* P, const float* Dg, float* ssq_o, int G, int bid) {
;     ...
; #pragma unroll
;             for (int k2 = 0; k2 < 2; ++k2) {
;                 const f32x4 dd = *(const LAS f32x4*)(sb + H3_D + (32 * kq + 16 * k2 + 4 * fq) * 4);
;                 S[k2] = S[k2] * dd;
;                 const LAS unsigned char* kp = sb + H3_K + (32 * kq + 16 * k2 + lv) * H3_KP + 4 * fq * 2;
;                 const s16x4 a0 = *(const LAS s16x4*)kp, a1 = *(const LAS s16x4*)(kp + 32);
;                 S[k2] = __builtin_amdgcn_mfma_f32_16x16x16bf16_1k(a0, vf0, S[k2], 0, 0, 0);
;                 S[k2] = __builtin_amdgcn_mfma_f32_16x16x16bf16_1k(a1, vf1, S[k2], 0, 0, 0);
;             }
;             { LAS float* ot = (LAS float*)(lds + H3_O + st * H3_OBYTES) + kq * 1024 + 16 * vt + lv;
; #pragma unroll
;               for (int i = 0; i < 4; ++i) { ot[(4 * fq + i) * 32] = o0[i]; ot[(16 + 4 * fq + i) * 32] = o1[i]; } }
;             LDS_BARRIER();
.LBB0_550:
	s_or_b64 exec, exec, s[56:57]
	s_nop 0
	s_nop 0
	s_nop 0
	v_add_u32_e32 v72, 64, v72
	v_lshl_add_u64 v[74:75], v[74:75], 0, s[46:47]
	v_lshl_add_u64 v[76:77], v[76:77], 0, s[48:49]
	s_waitcnt lgkmcnt(2)
	v_mul_f32_e32 v30, v30, v146
	v_mul_f32_e32 v31, v31, v147
	v_mul_f32_e32 v28, v28, v144
	v_mul_f32_e32 v29, v29, v145
	s_nop 0
	s_waitcnt lgkmcnt(1)
	v_mul_f32_e32 v26, v26, v150
	v_mul_f32_e32 v27, v27, v151
	v_mul_f32_e32 v24, v24, v148
	v_mul_f32_e32 v25, v25, v149
	v_mfma_f32_16x16x16_bf16 v[28:31], v[140:141], v[78:79], v[28:31]
	ds_write2_b32 v110, v32, v33 offset1:32
	ds_write2_b32 v111, v36, v37 offset1:32
	ds_write2_b32 v110, v34, v35 offset0:64 offset1:96
	ds_write2_b32 v111, v38, v39 offset0:64 offset1:96
	s_waitcnt lgkmcnt(0)
	s_waitcnt lgkmcnt(4)
	v_mfma_f32_16x16x16_bf16 v[24:27], v[152:153], v[78:79], v[24:27]
	s_barrier
	s_and_b64 vcc, exec, s[54:55]
	v_mfma_f32_16x16x16_bf16 v[28:31], v[142:143], v[80:81], v[28:31]
	v_mfma_f32_16x16x16_bf16 v[24:27], v[154:155], v[80:81], v[24:27]
	s_cbranch_vccnz .LBB0_552
	s_mov_b32 s35, s33
	s_branch .LBB0_484

; #define LAS __attribute__((address_space(3)))
; __device__ __forceinline__ unsigned pk2(float lo, float hi) { return pg8::cvt_pk_bf16(lo, hi); }
; #define AT_LSTORE(buf_) do { AT_LSTORE_K(buf_); AT_LSTORE_V(buf_); } while (0)
; template <int MODE> __device__ __forceinline__ void attn_phase(LAS unsigned char* lds, const bf16_t* Q, const bf16_t* KF, const bf16_t* VT, bf16_t* O, const int* positions, const float* gq, int G, int bid) {
;     ...
;                     __builtin_amdgcn_sched_barrier(0);
; #pragma unroll
;                     for (int ks = 0; ks < 2; ++ks)
; #pragma unroll
;                         for (int db = 0; db < 4; ++db) o[db] = __builtin_amdgcn_mfma_f32_32x32x16_bf16(va[ks * 4 + db], pb[ks], o[db], 0, 0, 0);
;                     float ps1 = 0.f;
; #pragma unroll
;                     for (int i = 0; i < 16; ++i) { s1[i] = __builtin_amdgcn_exp2f(s1[i]); ps1 += s1[i]; }
; #pragma unroll
;                     for (int g = 0; g < 8; ++g) { __builtin_amdgcn_sched_group_barrier(0x008, 1, 0); __builtin_amdgcn_sched_group_barrier(0x002, 4, 0); }
;                     __builtin_amdgcn_sched_barrier(0);
;                     lsum += ps1;
; #pragma unroll
;                     for (int ks = 0; ks < 2; ++ks)
; #pragma unroll
;                         for (int db = 0; db < 4; ++db) va[ks * 4 + db] = *(const LAS bf16x8*)(vb + (32 * db + lq) * AT_VP + (16 * (ks + 2) + 8 * hi) * 2);
;                     if (more && MODE < 3) AT_LSTORE((kt + 1) & 1);
;                     __builtin_amdgcn_sched_barrier(0);
; #pragma unroll
;                     for (int ks = 0; ks < 2; ++ks)
; #pragma unroll
;                         for (int q = 0; q < 4; ++q) { const unsigned pk = pk2(s1[8 * ks + 2 * q], s1[8 * ks + 2 * q + 1]); pb[ks][2 * q] = (short)(pk & 0xffff); pb[ks][2 * q + 1] = (short)(pk >> 16); }
;                     __builtin_amdgcn_sched_barrier(0);
; #pragma unroll
;                     for (int ks = 0; ks < 2; ++ks)
; #pragma unroll
;                         for (int db = 0; db < 4; ++db) o[db] = __builtin_amdgcn_mfma_f32_32x32x16_bf16(va[ks * 4 + db], pb[ks], o[db], 0, 0, 0);
.LBB0_673:
	v_cvt_pk_bf16_f32 v246, v196, v197
	v_cvt_pk_bf16_f32 v247, v194, v195
	v_cvt_pk_bf16_f32 v248, v192, v193
	v_cvt_pk_bf16_f32 v249, v198, v199
	v_cvt_pk_bf16_f32 v186, v186, v187
	v_cvt_pk_bf16_f32 v187, v190, v191
	v_cvt_pk_bf16_f32 v188, v188, v189
	v_cvt_pk_bf16_f32 v189, v184, v185
	s_nop 0
	s_waitcnt lgkmcnt(7)
	v_mfma_f32_32x32x16_bf16 v[64:79], v[180:183], v[246:249], v[64:79]
	v_exp_f32_e32 v180, v80
	v_exp_f32_e32 v181, v81
	v_exp_f32_e32 v182, v82
	v_exp_f32_e32 v183, v83
	v_add_f32_e32 v15, 0, v180
	v_add_f32_e32 v15, v181, v15
	v_add_f32_e32 v15, v182, v15
	v_add_f32_e32 v15, v183, v15
	s_waitcnt lgkmcnt(5)
	v_mfma_f32_32x32x16_bf16 v[48:63], v[176:179], v[246:249], v[48:63]
	v_exp_f32_e32 v176, v84
	v_exp_f32_e32 v177, v85
	v_exp_f32_e32 v178, v86
	v_exp_f32_e32 v179, v87
	v_add_f32_e32 v15, v176, v15
	v_add_f32_e32 v15, v177, v15
	v_add_f32_e32 v15, v178, v15
	v_add_f32_e32 v15, v179, v15
	s_waitcnt lgkmcnt(3)
	v_mfma_f32_32x32x16_bf16 v[32:47], v[172:175], v[246:249], v[32:47]
	v_exp_f32_e32 v172, v88
	v_exp_f32_e32 v173, v89
	v_exp_f32_e32 v174, v90
	v_exp_f32_e32 v175, v91
	v_add_f32_e32 v15, v172, v15
	v_add_f32_e32 v15, v173, v15
	v_add_f32_e32 v15, v174, v15
	v_add_f32_e32 v15, v175, v15
	s_waitcnt lgkmcnt(1)
	v_mfma_f32_32x32x16_bf16 v[16:31], v[168:171], v[246:249], v[16:31]
	v_exp_f32_e32 v184, v92
	v_exp_f32_e32 v185, v93
	v_exp_f32_e32 v190, v94
	v_add_f32_e32 v15, v184, v15
	v_add_f32_e32 v15, v185, v15
	v_add_f32_e32 v217, v190, v15
	v_mfma_f32_32x32x16_bf16 v[64:79], v[100:103], v[186:189], v[64:79]
	v_exp_f32_e32 v15, v95
	v_mfma_f32_32x32x16_bf16 v[48:63], v[104:107], v[186:189], v[48:63]
	v_mfma_f32_32x32x16_bf16 v[32:47], v[108:111], v[186:189], v[32:47]
	s_waitcnt lgkmcnt(0)
	v_mfma_f32_32x32x16_bf16 v[16:31], v[96:99], v[186:189], v[16:31]
	s_bitcmp1_b32 s7, 0
	s_cselect_b32 s22, 0xac00, 0
	ds_read_b128 v[80:83], v245 offset:25664
	ds_read_b128 v[84:87], v245 offset:25696
	ds_read_b128 v[88:91], v245 offset:30272
	ds_read_b128 v[92:95], v245 offset:30304
	ds_read_b128 v[96:99], v245 offset:34880
	ds_read_b128 v[100:103], v245 offset:34912
	ds_read_b128 v[104:107], v245 offset:39488
	ds_read_b128 v[108:111], v245 offset:39520
	s_add_i32 s22, s22, 0
	v_add_f32_e32 v168, v14, v216
	v_add_f32_e32 v169, v15, v217
	v_add_u32_e32 v14, s22, v200
	s_waitcnt vmcnt(4)
	ds_write_b128 v14, v[10:13]
	s_waitcnt vmcnt(3)
	ds_write_b128 v14, v[160:163] offset:128
	s_waitcnt vmcnt(2)
	ds_write_b128 v14, v[164:167] offset:256
	v_add_u32_e32 v14, s22, v222
	v_add_f32_e32 v216, v168, v169
	v_add_u32_e32 v168, 0x6000, v14
	v_add_u32_e32 v14, 0x8800, v14
	s_waitcnt vmcnt(1)
	ds_write2_b64 v168, v[6:7], v[8:9] offset0:128 offset1:130
	s_waitcnt vmcnt(0)
	ds_write2_b64 v14, v[2:3], v[4:5] offset1:2
	v_cvt_pk_bf16_f32 v168, v180, v181
	v_cvt_pk_bf16_f32 v169, v182, v183
	v_cvt_pk_bf16_f32 v170, v176, v177
	v_cvt_pk_bf16_f32 v171, v178, v179
	v_cvt_pk_bf16_f32 v172, v172, v173
	v_cvt_pk_bf16_f32 v173, v174, v175
	v_cvt_pk_bf16_f32 v174, v184, v185
	v_cvt_pk_bf16_f32 v175, v190, v15
	s_waitcnt lgkmcnt(12)
	s_setprio 1
	v_mfma_f32_32x32x16_bf16 v[64:79], v[80:83], v[168:171], v[64:79]
	s_waitcnt lgkmcnt(10)
	v_mfma_f32_32x32x16_bf16 v[48:63], v[88:91], v[168:171], v[48:63]
	s_waitcnt lgkmcnt(8)
	v_mfma_f32_32x32x16_bf16 v[32:47], v[96:99], v[168:171], v[32:47]
	s_waitcnt lgkmcnt(6)
	v_mfma_f32_32x32x16_bf16 v[16:31], v[104:107], v[168:171], v[16:31]
	v_mfma_f32_32x32x16_bf16 v[64:79], v[84:87], v[172:175], v[64:79]
	v_mfma_f32_32x32x16_bf16 v[48:63], v[92:95], v[172:175], v[48:63]
	v_mfma_f32_32x32x16_bf16 v[32:47], v[100:103], v[172:175], v[32:47]
	s_waitcnt lgkmcnt(5)
	v_mfma_f32_32x32x16_bf16 v[16:31], v[108:111], v[172:175], v[16:31]
	s_setprio 0
